# in-proj epilogue reads the row-panel sums of squares from LDS (loaded once per phase) instead of a global round trip per tile
# baseline (speedup 1.0000x reference)
.LBB0_256:
	s_add_u32 s50, s22, 0x7000000
	s_addc_u32 s51, s23, 0
	s_add_u32 s52, s22, 0x1500000
	s_addc_u32 s53, s23, 0
	v_readlane_b32 s2, v252, 22
	s_add_u32 s26, s22, 0x6000000
	v_readlane_b32 s3, v252, 23
	s_addc_u32 s27, s23, 0
	s_lshl_b64 s[28:29], s[2:3], 2
	s_add_u32 s2, s22, s28
	s_addc_u32 s3, s23, s29
	s_add_u32 s54, s2, 0x1400000
	s_addc_u32 s55, s3, 0
	v_readlane_b32 s100, v253, 54
	s_nop 3
	v_lshl_add_u32 v255, s100, 8, v184
	v_lshlrev_b32_e32 v255, 2, v255
	global_load_dword v254, v255, s[54:55]
	v_readlane_b32 s2, v252, 24
	v_readlane_b32 s3, v252, 25
	s_lshl_b64 s[28:29], s[2:3], 2
	s_add_u32 s22, s22, s28
	s_addc_u32 s23, s23, s29
	s_lshl_b32 s80, s16, 3
	s_lshl_b64 s[28:29], s[80:81], 2
	s_add_u32 s56, s20, s28
	s_addc_u32 s57, s21, s29
	s_and_b32 s2, s25, 3
	s_add_i32 m0, s14, 0x18000
	v_lshl_add_u64 v[4:5], v[4:5], 0, s[84:85]
	s_lshl_b32 s80, s18, 6
	s_lshl_b32 s3, s18, 13
	s_lshl_b32 s28, s2, 12
	s_waitcnt vmcnt(2)
	s_barrier
	global_load_lds_dwordx4 v[4:5], off
	v_lshl_add_u64 v[2:3], v[2:3], 0, s[84:85]
	s_add_i32 m0, s14, 0x1a000
	s_add_i32 s18, s14, 0x8000
	s_add_i32 s19, s14, 0xa000
	global_load_lds_dwordx4 v[2:3], off
	v_lshl_add_u64 v[0:1], v[0:1], 0, s[84:85]
	s_mov_b32 m0, s18
	s_add_u32 s20, s34, 0x40080
	global_load_lds_dwordx4 v[0:1], off
	v_lshl_add_u64 v[0:1], v[6:7], 0, s[84:85]
	s_mov_b32 m0, s19
	s_addc_u32 s21, s35, 0
	global_load_lds_dwordx4 v[0:1], off
	s_add_i32 m0, s14, 0x1c000
	v_lshl_add_u64 v[0:1], s[20:21], 0, v[140:141]
	global_load_lds_dwordx4 v[0:1], off
	v_lshl_add_u64 v[0:1], s[20:21], 0, v[136:137]
	s_add_i32 m0, s14, 0x1e000
	v_and_b32_e32 v145, 15, v8
	global_load_lds_dwordx4 v[0:1], off
	v_bfe_u32 v1, v8, 4, 2
	v_lshlrev_b32_e32 v2, 3, v1
	v_lshrrev_b32_e32 v0, 4, v8
	v_lshlrev_b32_e32 v1, 4, v1
	v_lshlrev_b32_e32 v3, 2, v8
	v_lshl_or_b32 v144, s2, 5, v2
	v_lshl_or_b32 v1, v145, 6, v1
	v_and_b32_e32 v3, 32, v3
	v_lshlrev_b32_e32 v190, 2, v144
	v_bitop3_b32 v0, s25, v0, 3 bitop3:0xa8
	v_bitop3_b32 v4, v1, s3, v3 bitop3:0xde
	v_bitop3_b32 v177, v1, s28, v3 bitop3:0xde
	v_cmp_eq_u32_e64 s[38:39], 0, v0
	v_lshl_add_u64 v[0:1], s[22:23], 0, v[190:191]
	s_mov_b64 s[22:23], 0x1480000
	v_lshl_add_u64 v[148:149], v[0:1], 0, s[22:23]
	v_lshlrev_b32_e32 v0, 14, v13
	v_and_b32_e32 v0, 0xffff8000, v0
	v_lshl_add_u32 v0, v12, 11, v0
	v_and_b32_e32 v1, 1, v13
	v_lshl_or_b32 v0, v1, 6, v0
	v_lshl_add_u32 v152, v14, 1, v0
	v_lshlrev_b32_e32 v0, 14, v9
	v_and_b32_e32 v0, 0xffff8000, v0
	s_waitcnt vmcnt(6)
	v_lshl_add_u32 v0, v10, 11, v0
	v_and_b32_e32 v1, 1, v9
	s_cmpk_lt_u32 s24, 0x100
	v_lshl_add_u64 v[146:147], s[26:27], 0, v[190:191]
	v_or_b32_e32 v190, 0x200, v190
	v_lshl_or_b32 v0, v1, 6, v0
	v_readlane_b32 s2, v253, 54
	s_cselect_b64 s[20:21], -1, 0
	s_mov_b32 s48, 0
	v_lshl_add_u64 v[150:151], s[26:27], 0, v[190:191]
	v_mov_b32_e32 v153, v191
	v_lshl_add_u32 v154, v11, 1, v0
	v_mov_b32_e32 v155, v191
	v_add_u32_e32 v216, 0, v4
	v_readlane_b32 s49, v253, 52
	s_mov_b32 s42, s2
	s_mov_b32 s100, 0x20000
	v_lshl_add_u32 v255, v184, 2, s100
	ds_write_b32 v255, v254
	s_waitcnt lgkmcnt(0)
	s_barrier
	v_readlane_b32 s3, v253, 55
	s_branch .LBB0_259

.LBB0_269:
	s_lshl_b32 s23, s42, 8
	s_add_i32 s23, s23, s80
	v_or_b32_e32 v174, s23, v145
	v_ashrrev_i32_e32 v175, 31, v174
	s_mov_b32 s100, 0x20000
	v_and_b32_e32 v128, 0xff, v174
	v_lshl_add_u32 v128, v128, 2, s100
	ds_read_b32 v130, v128
	ds_read_b32 v131, v128 offset:64
	ds_read_b32 v132, v128 offset:128
	ds_read_b32 v133, v128 offset:192
	ds_read_b32 v134, v128 offset:512
	ds_read_b32 v135, v128 offset:576
	ds_read_b32 v156, v128 offset:640
	s_nop 0
	ds_read_b32 v128, v128 offset:704
	v_add_u32_e32 v164, 0x80, v174
	v_ashrrev_i32_e32 v165, 31, v164
	s_mov_b64 s[30:31], -1
	s_cmp_lg_u32 s49, 15
	s_waitcnt vmcnt(0) lgkmcnt(0)
	v_fmamk_f32 v129, v130, 0x3a800000, v192
	v_cmp_gt_f32_e32 vcc, s93, v129
	v_mul_f32_e32 v130, 0x4b800000, v129
	v_fmamk_f32 v128, v128, 0x3a800000, v192
	v_cndmask_b32_e32 v129, v129, v130, vcc
	v_rsq_f32_e32 v129, v129
	s_nop 0
	v_mul_f32_e32 v130, 0x45800000, v129
	v_cndmask_b32_e32 v172, v129, v130, vcc
	v_fmamk_f32 v129, v131, 0x3a800000, v192
	v_cmp_gt_f32_e32 vcc, s93, v129
	v_mul_f32_e32 v130, 0x4b800000, v129
	s_nop 0
	v_cndmask_b32_e32 v129, v129, v130, vcc
	v_rsq_f32_e32 v129, v129
	s_nop 0
	v_mul_f32_e32 v130, 0x45800000, v129
	v_cndmask_b32_e32 v170, v129, v130, vcc
	v_fmamk_f32 v129, v132, 0x3a800000, v192
	v_cmp_gt_f32_e32 vcc, s93, v129
	v_mul_f32_e32 v130, 0x4b800000, v129
	s_nop 0
	v_cndmask_b32_e32 v129, v129, v130, vcc
	v_rsq_f32_e32 v129, v129
	s_nop 0
	v_mul_f32_e32 v130, 0x45800000, v129
	v_cndmask_b32_e32 v168, v129, v130, vcc
	v_fmamk_f32 v129, v133, 0x3a800000, v192
	v_cmp_gt_f32_e32 vcc, s93, v129
	v_mul_f32_e32 v130, 0x4b800000, v129
	s_nop 0
	v_cndmask_b32_e32 v129, v129, v130, vcc
	v_rsq_f32_e32 v129, v129
	s_nop 0
	v_mul_f32_e32 v130, 0x45800000, v129
	v_cndmask_b32_e32 v166, v129, v130, vcc
	v_fmamk_f32 v129, v134, 0x3a800000, v192
	v_cmp_gt_f32_e32 vcc, s93, v129
	v_mul_f32_e32 v130, 0x4b800000, v129
	s_nop 0
	v_cndmask_b32_e32 v129, v129, v130, vcc
	v_rsq_f32_e32 v129, v129
	s_nop 0
	v_mul_f32_e32 v130, 0x45800000, v129
	v_cndmask_b32_e32 v162, v129, v130, vcc
	v_fmamk_f32 v129, v135, 0x3a800000, v192
	v_cmp_gt_f32_e32 vcc, s93, v129
	v_mul_f32_e32 v130, 0x4b800000, v129
	s_nop 0
	v_cndmask_b32_e32 v129, v129, v130, vcc
	v_rsq_f32_e32 v129, v129
	s_nop 0
	v_mul_f32_e32 v130, 0x45800000, v129
	v_cndmask_b32_e32 v160, v129, v130, vcc
	v_fmamk_f32 v129, v156, 0x3a800000, v192
	v_cmp_gt_f32_e32 vcc, s93, v129
	v_mul_f32_e32 v130, 0x4b800000, v129
	s_nop 0
	v_cndmask_b32_e32 v129, v129, v130, vcc
	v_rsq_f32_e32 v129, v129
	s_nop 0
	v_mul_f32_e32 v130, 0x45800000, v129
	v_cndmask_b32_e32 v158, v129, v130, vcc
	v_cmp_gt_f32_e32 vcc, s93, v128
	v_mul_f32_e32 v129, 0x4b800000, v128
	s_nop 0
	v_cndmask_b32_e32 v128, v128, v129, vcc
	v_rsq_f32_e32 v128, v128
	s_nop 0
	v_mul_f32_e32 v129, 0x45800000, v128
	v_cndmask_b32_e32 v156, v128, v129, vcc
	s_cbranch_scc1 .LBB0_272
	s_and_b64 vcc, exec, s[30:31]
	s_cbranch_vccnz .LBB0_477
